# static s_setprio 1 for waves 4-7 during the attention phase (reset to 0 after)
# baseline (speedup 1.0000x reference)
; #define LAS __attribute__((address_space(3)))
; #define IN(k) (((PH_MASK >> KIND(k)) & 1) && lo <= (k) && (k) < hi_ph)
; __global__ void __launch_bounds__(NWAVES * 64, 2) fwd_kernel(Args args) {
;     ...
;         for (int rep = 0; rep <= ((REP_MASK >> 2) & 1); ++rep) if (IN(pb + 1)) {
;             PHASE_IDS;
;             LAS float* tab = (LAS float*)(lds + TAB_OFF);
;             for (int i = tid; i < 8 * 15 * 32; i += NWAVES * 64) { const int h = i / 480, rem = i % 480, dr = rem >> 5, o = rem & 31;
;                 tab[i] = (o < 31) ? rpb[((size_t)(l * 8 + h) * 15 + dr) * 31 + o] * LOG2E : 0.f; }
.LBB0_246:
	v_readlane_b32 s12, v252, 3
	v_readlane_b32 s13, v252, 4
	s_cmp_le_i32 s12, s5
	s_cselect_b64 s[12:13], -1, 0
	s_and_b64 s[18:19], s[12:13], s[18:19]
	s_andn2_b64 vcc, exec, s[18:19]
	s_cbranch_vccnz .LBB0_367
	v_readlane_b32 s0, v252, 43
	s_nop 3
	s_cmp_lt_u32 s0, 0x100
	s_cbranch_scc1 .Latt_prio_done
	s_setprio 1
.Latt_prio_done:
	v_mbcnt_lo_u32_b32 v0, -1, 0
	v_mbcnt_hi_u32_b32 v0, -1, v0
	s_lshl_b32 s54, s76, 3
	s_nop 0
	v_add_u32_e32 v117, s0, v0
	s_movk_i32 s0, 0xf00
	s_nop 0
	v_cmp_gt_i32_e32 vcc, s0, v117
	s_and_saveexec_b64 s[16:17], vcc
	s_cbranch_execz .LBB0_252
	s_add_i32 s0, 0, 0x20400
	v_lshl_add_u32 v2, v117, 2, s0
	s_mov_b64 s[30:31], 0
	v_mov_b32_e32 v3, v117
	s_branch .LBB0_250

; __device__ __forceinline__ int lane_now() { int l; asm volatile("v_mbcnt_lo_u32_b32 %0, -1, 0\n\tv_mbcnt_hi_u32_b32 %0, -1, %0" : "=v"(l)); return l; }
; __device__ __forceinline__ unsigned xb_add(unsigned* p, unsigned v) { return __hip_atomic_fetch_add(p, v, __ATOMIC_RELAXED, __HIP_MEMORY_SCOPE_AGENT); }
; __device__ __forceinline__ void xcd_barrier(const XcdBarrier& b, int wv) {
;     asm volatile("s_waitcnt vmcnt(0)" ::: "memory");
;     __syncthreads();
;     if (wv == 0 && lane_now() == 0) {
;         unsigned* bar = b.bar;
;         __builtin_amdgcn_s_waitcnt(0);
;         unsigned nloc = b.st[0], nx = b.st[1];
;         if (nloc == 0u) { xcd_barrier_complete(bar, b.x, nloc, nx); b.st[0] = nloc; b.st[1] = nx; }
;         const unsigned old = xb_add(&bar[XB_XSUB(b.x)], 1u);
.LBB0_367:
	s_setprio 0
	s_mul_i32 s0, s76, 5
	v_readlane_b32 s12, v252, 3
	s_add_i32 s5, s0, 3
	v_readlane_b32 s13, v252, 4
	s_cmp_lt_i32 s5, s13
	s_cselect_b64 s[16:17], -1, 0
	s_and_b64 s[12:13], s[18:19], s[16:17]
	s_andn2_b64 vcc, exec, s[12:13]
	s_cbranch_vccnz .LBB0_423
	s_waitcnt vmcnt(0)
	v_readlane_b32 s12, v255, 7
	v_readlane_b32 s13, v255, 8
	s_and_b64 vcc, exec, s[12:13]
	s_waitcnt lgkmcnt(0)
	s_barrier
	s_cbranch_vccnz .LBB0_422
	v_mbcnt_lo_u32_b32 v0, -1, 0
	v_mbcnt_hi_u32_b32 v0, -1, v0
	s_nop 0
	v_cmp_eq_u32_e32 vcc, 0, v0
	s_and_saveexec_b64 s[18:19], vcc
	s_cbranch_execz .LBB0_421
	v_readlane_b32 s0, v254, 63
	s_waitcnt vmcnt(0) expcnt(0) lgkmcnt(0)
	s_nop 0
	v_mov_b32_e32 v0, s0
	ds_read_b32 v3, v0
	v_readlane_b32 s0, v255, 0
	s_waitcnt lgkmcnt(0)
	v_cmp_ne_u32_e32 vcc, 0, v3
	v_mov_b32_e32 v0, s0
	ds_read_b32 v2, v0
	s_cbranch_vccnz .LBB0_385
	v_readlane_b32 s14, v252, 0
	v_readlane_b32 s15, v252, 1
	s_load_dwordx2 s[12:13], s[14:15], 0x4
	s_mov_b32 s10, 1
	s_waitcnt lgkmcnt(0)
	s_mul_i32 s0, s12, s72
	s_mul_i32 s0, s0, s13
	s_branch .LBB0_373
